# k46 + non-last local arrivers of the four remaining grid barriers issue an L2 writeback while they wait (pre-flush for the XCD leader)
# baseline (speedup 1.0000x reference)
.LBB0_56:
	s_or_b64 exec, exec, s[10:11]
	v_cvt_f32_u32_e32 v4, v2
	s_waitcnt vmcnt(0)
	v_readfirstlane_b32 s3, v3
	v_sub_u32_e32 v3, 0, v2
	v_rcp_iflag_f32_e32 v4, v4
	v_add_u32_e32 v5, s3, v1
	v_mul_f32_e32 v4, 0x4f7ffffe, v4
	v_cvt_u32_f32_e32 v4, v4
	v_mul_lo_u32 v1, v3, v4
	v_mul_hi_u32 v1, v4, v1
	v_add_u32_e32 v1, v4, v1
	v_mul_hi_u32 v1, v5, v1
	v_mul_lo_u32 v3, v1, v2
	v_sub_u32_e32 v3, v5, v3
	v_add_u32_e32 v4, 1, v1
	v_cmp_ge_u32_e32 vcc, v3, v2
	s_nop 1
	v_cndmask_b32_e32 v1, v1, v4, vcc
	v_sub_u32_e32 v4, v3, v2
	v_cndmask_b32_e32 v3, v3, v4, vcc
	v_add_u32_e32 v4, 1, v1
	v_cmp_ge_u32_e32 vcc, v3, v2
	v_add_u32_e32 v3, 1, v5
	s_nop 0
	v_cndmask_b32_e32 v1, v1, v4, vcc
	v_mul_lo_u32 v4, v2, v1
	v_add_u32_e32 v2, v4, v2
	v_cmp_ne_u32_e32 vcc, v3, v2
	s_and_saveexec_b64 s[8:9], vcc
	s_xor_b64 s[8:9], exec, s[8:9]
	s_cbranch_execz .LBB0_70
	buffer_wbl2 sc1
	s_waitcnt lgkmcnt(0)
	v_mov_b32_e32 v0, 0x2000
	global_load_dword v0, v0, s[6:7] offset:1024 sc1
	s_add_u32 s18, s6, 0x2400
	s_addc_u32 s19, s7, 0
	s_waitcnt vmcnt(0)
	v_cmp_eq_u32_e32 vcc, v0, v1
	s_and_saveexec_b64 s[10:11], vcc
	s_cbranch_execz .LBB0_69
	s_add_u32 s16, s0, 0x4200
	s_addc_u32 s17, s1, 0
	s_mov_b32 s3, 1
	s_mov_b64 s[20:21], 0
	v_mov_b32_e32 v0, 0
	s_branch .LBB0_60

.LBB0_376:
	s_or_b64 exec, exec, s[10:11]
	v_cvt_f32_u32_e32 v4, v2
	s_waitcnt vmcnt(0)
	v_readfirstlane_b32 s8, v3
	v_sub_u32_e32 v3, 0, v2
	v_rcp_iflag_f32_e32 v4, v4
	v_add_u32_e32 v5, s8, v1
	v_mul_f32_e32 v4, 0x4f7ffffe, v4
	v_cvt_u32_f32_e32 v4, v4
	v_mul_lo_u32 v1, v3, v4
	v_mul_hi_u32 v1, v4, v1
	v_add_u32_e32 v1, v4, v1
	v_mul_hi_u32 v1, v5, v1
	v_mul_lo_u32 v3, v1, v2
	v_sub_u32_e32 v3, v5, v3
	v_add_u32_e32 v4, 1, v1
	v_cmp_ge_u32_e32 vcc, v3, v2
	s_nop 1
	v_cndmask_b32_e32 v1, v1, v4, vcc
	v_sub_u32_e32 v4, v3, v2
	v_cndmask_b32_e32 v3, v3, v4, vcc
	v_add_u32_e32 v4, 1, v1
	v_cmp_ge_u32_e32 vcc, v3, v2
	v_add_u32_e32 v3, 1, v5
	s_nop 0
	v_cndmask_b32_e32 v1, v1, v4, vcc
	v_mul_lo_u32 v4, v2, v1
	v_add_u32_e32 v2, v4, v2
	v_cmp_ne_u32_e32 vcc, v3, v2
	s_and_saveexec_b64 s[8:9], vcc
	s_xor_b64 s[8:9], exec, s[8:9]
	s_cbranch_execz .LBB0_390
	buffer_wbl2 sc1
	s_waitcnt lgkmcnt(0)
	v_mov_b32_e32 v0, 0x2000
	global_load_dword v0, v0, s[6:7] offset:1024 sc1
	s_add_u32 s18, s6, 0x2400
	s_addc_u32 s19, s7, 0
	s_waitcnt vmcnt(0)
	v_cmp_eq_u32_e32 vcc, v0, v1
	s_and_saveexec_b64 s[10:11], vcc
	s_cbranch_execz .LBB0_389
	s_add_u32 s16, s0, 0x4200
	s_addc_u32 s17, s1, 0
	s_mov_b32 s13, 1
	s_mov_b64 s[20:21], 0
	v_mov_b32_e32 v0, 0
	s_branch .LBB0_380

.LBB0_613:
	s_or_b64 exec, exec, s[12:13]
	v_cvt_f32_u32_e32 v4, v2
	s_waitcnt vmcnt(0)
	v_readfirstlane_b32 s10, v3
	v_sub_u32_e32 v3, 0, v2
	v_rcp_iflag_f32_e32 v4, v4
	v_add_u32_e32 v5, s10, v1
	v_mul_f32_e32 v4, 0x4f7ffffe, v4
	v_cvt_u32_f32_e32 v4, v4
	v_mul_lo_u32 v1, v3, v4
	v_mul_hi_u32 v1, v4, v1
	v_add_u32_e32 v1, v4, v1
	v_mul_hi_u32 v1, v5, v1
	v_mul_lo_u32 v3, v1, v2
	v_sub_u32_e32 v3, v5, v3
	v_add_u32_e32 v4, 1, v1
	v_cmp_ge_u32_e32 vcc, v3, v2
	s_nop 1
	v_cndmask_b32_e32 v1, v1, v4, vcc
	v_sub_u32_e32 v4, v3, v2
	v_cndmask_b32_e32 v3, v3, v4, vcc
	v_add_u32_e32 v4, 1, v1
	v_cmp_ge_u32_e32 vcc, v3, v2
	v_add_u32_e32 v3, 1, v5
	s_nop 0
	v_cndmask_b32_e32 v1, v1, v4, vcc
	v_mul_lo_u32 v4, v2, v1
	v_add_u32_e32 v2, v4, v2
	v_cmp_ne_u32_e32 vcc, v3, v2
	s_and_saveexec_b64 s[10:11], vcc
	s_xor_b64 s[10:11], exec, s[10:11]
	s_cbranch_execz .LBB0_627
	buffer_wbl2 sc1
	s_waitcnt lgkmcnt(0)
	v_mov_b32_e32 v0, 0x2000
	global_load_dword v0, v0, s[8:9] offset:1024 sc1
	s_add_u32 s18, s8, 0x2400
	s_addc_u32 s19, s9, 0
	s_waitcnt vmcnt(0)
	v_cmp_eq_u32_e32 vcc, v0, v1
	s_and_saveexec_b64 s[12:13], vcc
	s_cbranch_execz .LBB0_626
	s_add_u32 s16, s0, 0x4200
	s_addc_u32 s17, s1, 0
	s_mov_b32 s14, 1
	s_mov_b64 s[20:21], 0
	v_mov_b32_e32 v0, 0
	s_branch .LBB0_617

.LBB0_902:
	s_or_b64 exec, exec, s[16:17]
	v_cvt_f32_u32_e32 v4, v2
	s_waitcnt vmcnt(0)
	v_readfirstlane_b32 s12, v3
	v_sub_u32_e32 v3, 0, v2
	v_rcp_iflag_f32_e32 v4, v4
	v_add_u32_e32 v5, s12, v1
	v_mul_f32_e32 v4, 0x4f7ffffe, v4
	v_cvt_u32_f32_e32 v4, v4
	v_mul_lo_u32 v1, v3, v4
	v_mul_hi_u32 v1, v4, v1
	v_add_u32_e32 v1, v4, v1
	v_mul_hi_u32 v1, v5, v1
	v_mul_lo_u32 v3, v1, v2
	v_sub_u32_e32 v3, v5, v3
	v_add_u32_e32 v4, 1, v1
	v_cmp_ge_u32_e32 vcc, v3, v2
	s_nop 1
	v_cndmask_b32_e32 v1, v1, v4, vcc
	v_sub_u32_e32 v4, v3, v2
	v_cndmask_b32_e32 v3, v3, v4, vcc
	v_add_u32_e32 v4, 1, v1
	v_cmp_ge_u32_e32 vcc, v3, v2
	v_add_u32_e32 v3, 1, v5
	s_nop 0
	v_cndmask_b32_e32 v1, v1, v4, vcc
	v_mul_lo_u32 v4, v2, v1
	v_add_u32_e32 v2, v4, v2
	v_cmp_ne_u32_e32 vcc, v3, v2
	s_and_saveexec_b64 s[12:13], vcc
	s_xor_b64 s[12:13], exec, s[12:13]
	s_cbranch_execz .LBB0_916
	buffer_wbl2 sc1
	s_waitcnt lgkmcnt(0)
	v_mov_b32_e32 v0, 0x2000
	global_load_dword v0, v0, s[10:11] offset:1024 sc1
	s_add_u32 s18, s10, 0x2400
	s_addc_u32 s19, s11, 0
	s_waitcnt vmcnt(0)
	v_cmp_eq_u32_e32 vcc, v0, v1
	s_and_saveexec_b64 s[16:17], vcc
	s_cbranch_execz .LBB0_915
	s_mov_b32 s14, 1
	s_mov_b64 s[22:23], 0
	v_mov_b32_e32 v0, 0
	s_branch .LBB0_906
